# a1 task prologue: IQ rows, head weights and first key tile fragments loaded in one round trip instead of three
# baseline (speedup 1.0000x reference)
; DI float bf2f(bf16_t b) { return __uint_as_float(((unsigned)b) << 16); }
; DI int pi_row(int r) { return (r & 3) | (((r >> 3) & 1) << 2) | (((r >> 2) & 1) << 3) | (r & 16); }
; DI void a1_task(unsigned char* shm, const bf16_t* prm, const bf16_t* prt, unsigned* mask, int b, int qt, const int tid) {
;     ...
;     { u32x4 t[4];
; #pragma unroll
;       for (int p = 0; p < 4; ++p) { const int c = tid + p * 512, row = c >> 6, ch = c & 63; t[p] = *(const u32x4*)(prm + (size_t)(tok0 + t0 + row) * RM_LD + C_IQ + ch * 8); }
; #pragma unroll
;       for (int p = 0; p < 4; ++p) { const int c = tid + p * 512, row = c >> 6, ch = c & 63; *(u32x4*)(shm + row * 1040 + ch * 16) = t[p]; } }
;     cnt[tid] = 0u; cnt[tid + 512] = 0u;
;     float* wqs = (float*)(shm + 33280 + 4096);
;     if (tid < 256) wqs[tid] = bf2f(prt[(size_t)(R_IW + (tid >> 5)) * MTOK + tok0 + t0 + (tid & 31)]);
;     __syncthreads();
;     unsigned key[8][16];
;     const bf16_t* kp = prm + (size_t)(tok0 + pi_row(r)) * RM_LD + C_IK + 8 * h;
;     bf16x8 kf[4];
;     if (wid <= qt) {
; #pragma unroll
;         for (int ks = 0; ks < 4; ++ks) kf[ks] = *(const bf16x8*)(kp + (size_t)(wid * 32) * RM_LD + 16 * ks);
;     }
.LBB0_380:
	s_andn2_b64 vcc, exec, s[0:1]
	s_mov_b64 s[0:1], -1
	s_cbranch_vccnz .LBB0_372
	v_readlane_b32 s1, v255, 35
	s_lshl_b32 s0, s2, 5
	s_lshl_b32 s4, s1, 11
	s_add_i32 s5, s0, s4
	v_add_u32_e32 v0, s5, v112
	s_movk_i32 s1, 0x1600
	v_mad_i64_i32 v[2:3], s[6:7], v0, s1, v[104:105]
	v_add_u32_e32 v0, s5, v113
	v_mad_i64_i32 v[6:7], s[6:7], v0, s1, v[104:105]
	v_add_u32_e32 v0, s5, v114
	v_mad_i64_i32 v[10:11], s[6:7], v0, s1, v[104:105]
	v_add_u32_e32 v0, s5, v115
	v_mad_i64_i32 v[14:15], s[6:7], v0, s1, v[104:105]
	global_load_dwordx4 v[2:5], v[2:3], off offset:896
	s_nop 0
	global_load_dwordx4 v[6:9], v[6:7], off offset:896
	s_nop 0
	global_load_dwordx4 v[10:13], v[10:11], off offset:896
	s_nop 0
	global_load_dwordx4 v[14:17], v[14:15], off offset:896
	v_writelane_b32 v255, s5, 37
	v_readfirstlane_b32 s8, v210
	s_mov_b64 s[42:43], exec
	v_readlane_b32 s38, v255, 29
	v_readlane_b32 s39, v255, 30
	s_and_b64 s[38:39], s[42:43], s[38:39]
	s_mov_b64 exec, s[38:39]
	s_cbranch_execz .Lt_nw
	s_ashr_i32 s5, s4, 31
	v_lshl_add_u64 v[18:19], s[4:5], 1, v[102:103]
	s_ashr_i32 s1, s0, 31
	v_lshl_add_u64 v[18:19], s[0:1], 1, v[18:19]
	v_lshlrev_b32_e32 v20, 1, v100
	v_mov_b32_e32 v21, 0
	v_lshl_add_u64 v[18:19], v[18:19], 0, v[20:21]
	global_load_ushort v20, v[18:19], off
.Lt_nw:
	s_mov_b64 exec, s[42:43]
	s_ashr_i32 s6, s8, 6
	v_or_b32_e32 v0, s4, v117
	s_movk_i32 s1, 0x1600
	s_nop 0
	v_mad_i64_i32 v[108:109], s[4:5], v0, s1, v[106:107]
	s_cmp_lt_i32 s2, s6
	s_cbranch_scc1 .Lt_nk
	s_lshl_b32 s1, s6, 5
	s_nop 0
	v_mad_i64_i32 v[22:23], s[4:5], s1, v241, v[108:109]
	global_load_dwordx4 v[50:53], v[22:23], off offset:1920
	global_load_dwordx4 v[54:57], v[22:23], off offset:1952
	global_load_dwordx4 v[58:61], v[22:23], off offset:1984
	global_load_dwordx4 v[62:65], v[22:23], off offset:2016
.Lt_nk:
	s_waitcnt vmcnt(0)
	ds_write_b128 v137, v[2:5]
	ds_write_b128 v138, v[6:9]
	ds_write_b128 v139, v[10:13]
	ds_write_b128 v140, v[14:17]
	ds_write2st64_b32 v116, v1, v1 offset0:130 offset1:138
	s_mov_b64 exec, s[38:39]
	v_lshlrev_b32_e32 v20, 16, v20
	ds_write_b32 v116, v20 offset:37376
	s_mov_b64 exec, s[42:43]
	s_cmp_ge_i32 s2, s6
	s_cselect_b64 s[38:39], -1, 0
	s_waitcnt lgkmcnt(0)
	s_barrier
